# v33 + NSA selected loop: tile-stream DMA issue moved into the LDS-latency shadow before the first QK wait
# baseline (speedup 1.0000x reference)
; template <int MODE> __device__ __forceinline__ int pop_tile(unsigned& tiles) { int j; if (MODE == 2) { j = 31 - __builtin_clz(tiles); tiles &= ~(1u << j); } else { j = __builtin_ctz(tiles); tiles &= tiles - 1u; } return j; }
; __device__ __forceinline__ void nsa_unit(int b, int g, int tq, const Args& a, LAS unsigned char* lds, int tid, int wave, int lane, int& nxt) {
;     ...
;                 const int j2 = ut ? pop_tile<1>(ut) : -1;
;                 NL_DMA(1, (j2 >= 0 ? j2 : j0), o2);
.LBB0_981:
	v_sub_co_u32_e64 v2, s[6:7], s0, 1
	s_mov_b32 s11, s4
	s_mov_b32 s12, s50
	s_mov_b32 s50, s1
	s_ff1_i32_b32 s1, s0
	s_and_b64 s[4:5], s[6:7], exec
	s_cselect_b32 s44, s97, s1
	s_lshl_b64 s[100:101], s[44:45], 14
	v_readfirstlane_b32 s13, v2
	v_bfe_u32 v2, v164, s97, 1
	s_cmp_gt_i32 s97, s10
	v_cmp_eq_u32_e64 s[4:5], 0, v2
	s_mov_b64 s[8:9], -1
	s_cbranch_scc1 .LBB0_983
	s_add_i32 s8, s51, 0
	v_sub_f32_e32 v2, v185, v0
	v_add_u32_e32 v6, s8, v183
	v_cndmask_b32_e64 v112, v2, v173, s[4:5]
	ds_read_b128 v[2:5], v6
	ds_read_b128 v[6:9], v6 offset:4096
	v_mov_b32_e32 v113, v112
	v_mov_b32_e32 v114, v112
	v_mov_b32_e32 v115, v112
	v_mov_b32_e32 v116, v112
	v_mov_b32_e32 v117, v112
	v_mov_b32_e32 v118, v112
	v_mov_b32_e32 v119, v112
	v_mov_b32_e32 v120, v112
	v_mov_b32_e32 v121, v112
	v_mov_b32_e32 v122, v112
	v_mov_b32_e32 v123, v112
	v_mov_b32_e32 v124, v112
	v_mov_b32_e32 v125, v112
	v_mov_b32_e32 v126, v112
	v_mov_b32_e32 v127, v112
	v_add_u32_e32 v194, s8, v184
	v_add_u32_e32 v195, s8, v186
	v_add_u32_e32 v212, s8, v187
	ds_read_b128 v[196:199], v194
	ds_read_b128 v[200:203], v194 offset:4096
	ds_read_b128 v[204:207], v195
	ds_read_b128 v[208:211], v195 offset:4096
	ds_read_b128 v[216:219], v212
	ds_read_b128 v[220:223], v212 offset:4096
	s_mov_b64 s[8:9], 0
	v_lshl_add_u64 v[226:227], v[160:161], 0, s[100:101]
	s_add_i32 s98, s50, s94
	s_mov_b32 m0, s98
	s_nop 0
	global_load_lds_dwordx4 v[226:227], off
	v_lshl_add_u64 v[226:227], v[162:163], 0, s[100:101]
	s_add_i32 s98, s50, s95
	s_mov_b32 m0, s98
	s_nop 0
	global_load_lds_dwordx4 v[226:227], off
	s_waitcnt lgkmcnt(6)
	s_nop 0
	v_mfma_f32_32x32x16_bf16 v[128:143], v[2:5], v[144:147], v[112:127]
	v_mfma_f32_32x32x16_bf16 v[112:127], v[6:9], v[144:147], v[112:127]
	s_waitcnt lgkmcnt(4)
	v_mfma_f32_32x32x16_bf16 v[128:143], v[196:199], v[148:151], v[128:143]
	v_mfma_f32_32x32x16_bf16 v[112:127], v[200:203], v[148:151], v[112:127]
	s_waitcnt lgkmcnt(2)
	v_mfma_f32_32x32x16_bf16 v[128:143], v[204:207], v[152:155], v[128:143]
	v_mfma_f32_32x32x16_bf16 v[112:127], v[208:211], v[152:155], v[112:127]
	s_waitcnt lgkmcnt(0)
	v_mfma_f32_32x32x16_bf16 v[128:143], v[216:219], v[156:159], v[128:143]
	v_mfma_f32_32x32x16_bf16 v[112:127], v[220:223], v[156:159], v[112:127]
; #define LAS __attribute__((address_space(3)))
;     ...
;         } else { LAS const float* ab = aux + (t - kb + 1);
; #pragma unroll
;             for (int r = 0; r < 16; ++r) { X0[r] = ab[63 - ((r & 3) + 8 * (r >> 2))] - m; X1[r] = ab[31 - ((r & 3) + 8 * (r >> 2))] - m; }
;             if (MODE == 1 && !sel) {
; #pragma unroll
;                 for (int r = 0; r < 16; ++r) { X0[r] = NEG; X1[r] = NEG; } }
.LBB0_983:
	s_andn2_b64 vcc, exec, s[8:9]
	s_cbranch_vccnz .LBB0_985
	v_lshl_or_b32 v2, s97, 6, v179
	v_sub_u32_e32 v2, v178, v2
	s_nop 7
	v_lshl_add_u32 v126, v2, 2, s96
	ds_read2_b32 v[2:3], v126 offset0:63 offset1:64
	ds_read2_b32 v[4:5], v126 offset0:31 offset1:32
	ds_read2_b32 v[6:7], v126 offset0:61 offset1:62
	ds_read2_b32 v[8:9], v126 offset0:29 offset1:30
	s_add_i32 s8, s51, 0
	s_waitcnt lgkmcnt(3)
	v_sub_f32_e32 v10, v2, v0
	v_sub_f32_e32 v11, v3, v0
	ds_read2_b32 v[2:3], v126 offset0:55 offset1:56
	s_waitcnt lgkmcnt(3)
	v_sub_f32_e32 v12, v4, v0
	v_sub_f32_e32 v13, v5, v0
	ds_read2_b32 v[4:5], v126 offset0:23 offset1:24
	ds_read2_b32 v[116:117], v126 offset0:15 offset1:16
	ds_read2_b32 v[118:119], v126 offset0:13 offset1:14
	s_waitcnt lgkmcnt(3)
	v_sub_f32_e32 v112, v2, v0
	v_sub_f32_e32 v113, v3, v0
	ds_read2_b32 v[2:3], v126 offset0:21 offset1:22
	v_sub_f32_e32 v14, v8, v0
	v_sub_f32_e32 v15, v9, v0
	ds_read2_b32 v[8:9], v126 offset0:53 offset1:54
	ds_read2_b32 v[120:121], v126 offset0:39 offset1:40
	s_waitcnt lgkmcnt(5)
	v_sub_f32_e32 v114, v4, v0
	v_sub_f32_e32 v115, v5, v0
	ds_read2_b32 v[4:5], v126 offset0:47 offset1:48
	s_waitcnt lgkmcnt(3)
	v_sub_f32_e32 v190, v2, v0
	v_sub_f32_e32 v191, v3, v0
	ds_read2_b32 v[2:3], v126 offset0:45 offset1:46
	ds_read2_b32 v[122:123], v126 offset0:7 offset1:8
	ds_read2_b32 v[124:125], v126 offset0:37 offset1:38
	ds_read2_b32 v[126:127], v126 offset0:5 offset1:6
	s_waitcnt lgkmcnt(6)
	v_sub_f32_e32 v8, v8, v0
	v_sub_f32_e32 v9, v9, v0
	v_sub_f32_e32 v6, v6, v0
	v_sub_f32_e32 v7, v7, v0
	s_waitcnt lgkmcnt(4)
	v_sub_f32_e32 v4, v4, v0
	v_sub_f32_e32 v5, v5, v0
	s_waitcnt lgkmcnt(3)
	v_sub_f32_e32 v2, v2, v0
	v_sub_f32_e32 v3, v3, v0
	s_waitcnt lgkmcnt(1)
	v_sub_f32_e32 v130, v124, v0
	v_sub_f32_e32 v131, v125, v0
	v_cndmask_b32_e64 v135, v8, v173, s[4:5]
	v_add_u32_e32 v8, s8, v183
	v_cndmask_b32_e64 v143, v130, v173, s[4:5]
	v_cndmask_b32_e64 v142, v131, v173, s[4:5]
	v_cndmask_b32_e64 v139, v2, v173, s[4:5]
	v_cndmask_b32_e64 v138, v3, v173, s[4:5]
	v_cndmask_b32_e64 v137, v4, v173, s[4:5]
	v_cndmask_b32_e64 v136, v5, v173, s[4:5]
	ds_read_b128 v[2:5], v8
	v_cndmask_b32_e64 v134, v9, v173, s[4:5]
	v_cndmask_b32_e64 v131, v6, v173, s[4:5]
	v_cndmask_b32_e64 v130, v7, v173, s[4:5]
	ds_read_b128 v[6:9], v8 offset:4096
	v_sub_f32_e32 v116, v116, v0
	v_sub_f32_e32 v117, v117, v0
	v_sub_f32_e32 v118, v118, v0
	v_sub_f32_e32 v119, v119, v0
	v_sub_f32_e32 v128, v120, v0
	v_sub_f32_e32 v129, v121, v0
	v_sub_f32_e32 v120, v122, v0
	v_sub_f32_e32 v121, v123, v0
	s_waitcnt lgkmcnt(2)
	v_sub_f32_e32 v122, v126, v0
	v_sub_f32_e32 v123, v127, v0
	v_cndmask_b32_e64 v125, v120, v173, s[4:5]
	v_cndmask_b32_e64 v127, v122, v173, s[4:5]
	v_cndmask_b32_e64 v126, v123, v173, s[4:5]
	v_cndmask_b32_e64 v124, v121, v173, s[4:5]
	v_cndmask_b32_e64 v123, v118, v173, s[4:5]
	v_cndmask_b32_e64 v122, v119, v173, s[4:5]
	v_cndmask_b32_e64 v121, v116, v173, s[4:5]
	v_cndmask_b32_e64 v120, v117, v173, s[4:5]
	v_cndmask_b32_e64 v119, v190, v173, s[4:5]
	v_cndmask_b32_e64 v141, v128, v173, s[4:5]
	v_cndmask_b32_e64 v140, v129, v173, s[4:5]
	v_cndmask_b32_e64 v133, v112, v173, s[4:5]
	v_cndmask_b32_e64 v132, v113, v173, s[4:5]
	v_cndmask_b32_e64 v129, v10, v173, s[4:5]
	v_cndmask_b32_e64 v128, v11, v173, s[4:5]
	v_cndmask_b32_e64 v118, v191, v173, s[4:5]
	v_cndmask_b32_e64 v117, v114, v173, s[4:5]
	v_cndmask_b32_e64 v116, v115, v173, s[4:5]
	v_cndmask_b32_e64 v115, v14, v173, s[4:5]
	v_cndmask_b32_e64 v114, v15, v173, s[4:5]
	v_cndmask_b32_e64 v113, v12, v173, s[4:5]
	v_cndmask_b32_e64 v112, v13, v173, s[4:5]
	v_add_u32_e32 v194, s8, v184
	v_add_u32_e32 v195, s8, v186
	v_add_u32_e32 v212, s8, v187
	ds_read_b128 v[196:199], v194
	ds_read_b128 v[200:203], v194 offset:4096
	ds_read_b128 v[204:207], v195
	ds_read_b128 v[208:211], v195 offset:4096
	ds_read_b128 v[216:219], v212
	ds_read_b128 v[220:223], v212 offset:4096
	v_lshl_add_u64 v[226:227], v[160:161], 0, s[100:101]
	s_add_i32 s98, s50, s94
	s_mov_b32 m0, s98
	s_nop 0
	global_load_lds_dwordx4 v[226:227], off
	v_lshl_add_u64 v[226:227], v[162:163], 0, s[100:101]
	s_add_i32 s98, s50, s95
	s_mov_b32 m0, s98
	s_nop 0
	global_load_lds_dwordx4 v[226:227], off
	s_waitcnt lgkmcnt(6)
	v_mfma_f32_32x32x16_bf16 v[128:143], v[2:5], v[144:147], v[128:143]
	v_mfma_f32_32x32x16_bf16 v[112:127], v[6:9], v[144:147], v[112:127]
	s_waitcnt lgkmcnt(4)
	v_mfma_f32_32x32x16_bf16 v[128:143], v[196:199], v[148:151], v[128:143]
	v_mfma_f32_32x32x16_bf16 v[112:127], v[200:203], v[148:151], v[112:127]
	s_waitcnt lgkmcnt(2)
	v_mfma_f32_32x32x16_bf16 v[128:143], v[204:207], v[152:155], v[128:143]
	v_mfma_f32_32x32x16_bf16 v[112:127], v[208:211], v[152:155], v[112:127]
	s_waitcnt lgkmcnt(0)
	v_mfma_f32_32x32x16_bf16 v[128:143], v[216:219], v[156:159], v[128:143]
	v_mfma_f32_32x32x16_bf16 v[112:127], v[220:223], v[156:159], v[112:127]
